# k11 + grid barrier: cache invalidate issued on entry to the leader-lane section and waited for before the arrival add; none after the release
# baseline (speedup 1.0000x reference)
.LBB0_446:
	s_cmp_gt_i32 s97, 1
	s_cselect_b64 s[4:5], -1, 0
	s_and_b64 s[0:1], s[8:9], s[4:5]
	s_andn2_b64 vcc, exec, s[0:1]
	s_cbranch_vccnz .LBB0_500
	s_waitcnt vmcnt(0)
	s_barrier
	s_mov_b64 s[0:1], exec
	v_readlane_b32 s6, v238, 2
	v_readlane_b32 s7, v238, 3
	s_and_b64 s[6:7], s[0:1], s[6:7]
	s_mov_b64 exec, s[6:7]
	s_cbranch_execz .LBB0_499
	s_add_i32 s3, 0, 0x25480
	v_mov_b32_e32 v1, s3
	s_waitcnt vmcnt(0) expcnt(0) lgkmcnt(0)
	buffer_inv sc1
	ds_read_b32 v3, v1
	s_add_i32 s3, 0, 0x25484
	v_mov_b32_e32 v1, s3
	ds_read_b32 v1, v1
	s_waitcnt lgkmcnt(1)
	v_cmp_ne_u32_e32 vcc, 0, v3
	s_cbranch_vccnz .LBB0_463
	v_readlane_b32 s6, v238, 0
	v_readlane_b32 s7, v238, 1
	s_load_dwordx2 s[10:11], s[6:7], 0x4
	s_add_u32 s6, s42, 0x1000
	s_addc_u32 s7, s43, 0
	s_add_u32 s8, s42, 0x1100
	s_addc_u32 s9, s43, 0
	s_add_u32 s12, s42, 0x1200
	s_addc_u32 s13, s43, 0
	s_waitcnt lgkmcnt(0)
	s_mul_i32 s3, s10, s24
	s_add_u32 s14, s42, 0x1300
	s_mul_i32 s3, s3, s11
	s_addc_u32 s15, s43, 0
	s_mov_b32 s10, 1
	v_mov_b32_e32 v17, 0
	s_branch .LBB0_451

.LBB0_463:
	s_mov_b64 s[8:9], exec
	v_readlane_b32 s3, v238, 4
	s_lshl_b32 s3, s3, 8
	v_mbcnt_lo_u32_b32 v2, s8, 0
	s_add_u32 s6, s42, s3
	v_mbcnt_hi_u32_b32 v2, s9, v2
	s_addc_u32 s7, s43, 0
	v_cmp_eq_u32_e32 vcc, 0, v2
	s_and_saveexec_b64 s[12:13], vcc
	s_cbranch_execz .LBB0_465
	s_bcnt1_i32_b64 s3, s[8:9]
	v_mov_b32_e32 v4, 0x1000
	v_mov_b32_e32 v5, s3
	s_waitcnt vmcnt(0)
	global_atomic_add v4, v4, v5, s[6:7] offset:1024 sc0

.LBB0_539:
	s_cmp_gt_i32 s97, 2
	s_cselect_b64 s[4:5], -1, 0
	s_and_b64 s[0:1], s[0:1], s[4:5]
	s_andn2_b64 vcc, exec, s[0:1]
	s_cbranch_vccnz .LBB0_593
	s_waitcnt vmcnt(0)
	s_barrier
	s_mov_b64 s[0:1], exec
	v_readlane_b32 s6, v238, 2
	v_readlane_b32 s7, v238, 3
	s_and_b64 s[6:7], s[0:1], s[6:7]
	s_mov_b64 exec, s[6:7]
	s_cbranch_execz .LBB0_592
	s_add_i32 s3, 0, 0x25480
	v_mov_b32_e32 v1, s3
	s_waitcnt vmcnt(0) expcnt(0) lgkmcnt(0)
	buffer_inv sc1
	ds_read_b32 v3, v1
	s_add_i32 s3, 0, 0x25484
	v_mov_b32_e32 v1, s3
	ds_read_b32 v1, v1
	s_waitcnt lgkmcnt(1)
	v_cmp_ne_u32_e32 vcc, 0, v3
	s_cbranch_vccnz .LBB0_556
	v_readlane_b32 s6, v238, 0
	v_readlane_b32 s7, v238, 1
	s_load_dwordx2 s[10:11], s[6:7], 0x4
	s_add_u32 s6, s42, 0x1000
	s_addc_u32 s7, s43, 0
	s_add_u32 s8, s42, 0x1100
	s_addc_u32 s9, s43, 0
	s_add_u32 s12, s42, 0x1200
	s_addc_u32 s13, s43, 0
	s_waitcnt lgkmcnt(0)
	s_mul_i32 s3, s10, s24
	s_add_u32 s14, s42, 0x1300
	s_mul_i32 s3, s3, s11
	s_addc_u32 s15, s43, 0
	s_mov_b32 s10, 1
	v_mov_b32_e32 v17, 0
	s_branch .LBB0_544

.LBB0_603:
	s_cmp_gt_i32 s97, 3
	s_cselect_b64 s[4:5], -1, 0
	s_and_b64 s[0:1], s[0:1], s[4:5]
	s_andn2_b64 vcc, exec, s[0:1]
	s_cbranch_vccnz .LBB0_657
	s_waitcnt vmcnt(0)
	s_barrier
	s_mov_b64 s[0:1], exec
	v_readlane_b32 s6, v238, 2
	v_readlane_b32 s7, v238, 3
	s_and_b64 s[6:7], s[0:1], s[6:7]
	s_mov_b64 exec, s[6:7]
	s_cbranch_execz .LBB0_656
	s_add_i32 s3, 0, 0x25480
	v_mov_b32_e32 v1, s3
	s_waitcnt vmcnt(0) expcnt(0) lgkmcnt(0)
	buffer_inv sc1
	ds_read_b32 v3, v1
	s_add_i32 s3, 0, 0x25484
	v_mov_b32_e32 v1, s3
	ds_read_b32 v1, v1
	s_waitcnt lgkmcnt(1)
	v_cmp_ne_u32_e32 vcc, 0, v3
	s_cbranch_vccnz .LBB0_620
	v_readlane_b32 s6, v238, 0
	v_readlane_b32 s7, v238, 1
	s_load_dwordx2 s[10:11], s[6:7], 0x4
	s_add_u32 s6, s42, 0x1000
	s_addc_u32 s7, s43, 0
	s_add_u32 s8, s42, 0x1100
	s_addc_u32 s9, s43, 0
	s_add_u32 s12, s42, 0x1200
	s_addc_u32 s13, s43, 0
	s_waitcnt lgkmcnt(0)
	s_mul_i32 s3, s10, s24
	s_add_u32 s14, s42, 0x1300
	s_mul_i32 s3, s3, s11
	s_addc_u32 s15, s43, 0
	s_mov_b32 s10, 1
	v_mov_b32_e32 v17, 0
	s_branch .LBB0_608

.LBB0_1124:
	s_cmp_gt_i32 s97, 4
	s_cselect_b64 s[0:1], -1, 0
	s_and_b64 s[4:5], s[8:9], s[0:1]
	s_andn2_b64 vcc, exec, s[4:5]
	s_cbranch_vccnz .LBB0_1178
	s_waitcnt vmcnt(0)
	s_barrier
	s_mov_b64 s[4:5], exec
	v_readlane_b32 s6, v238, 2
	v_readlane_b32 s7, v238, 3
	s_and_b64 s[6:7], s[4:5], s[6:7]
	s_mov_b64 exec, s[6:7]
	s_cbranch_execz .LBB0_1177
	s_add_i32 s3, 0, 0x25480
	v_mov_b32_e32 v1, s3
	s_waitcnt vmcnt(0) expcnt(0) lgkmcnt(0)
	buffer_inv sc1
	ds_read_b32 v3, v1
	s_add_i32 s3, 0, 0x25484
	v_mov_b32_e32 v1, s3
	ds_read_b32 v1, v1
	s_waitcnt lgkmcnt(1)
	v_cmp_ne_u32_e32 vcc, 0, v3
	s_cbranch_vccnz .LBB0_1141
	v_readlane_b32 s6, v238, 0
	v_readlane_b32 s7, v238, 1
	s_load_dwordx2 s[10:11], s[6:7], 0x4
	s_add_u32 s6, s42, 0x1000
	s_addc_u32 s7, s43, 0
	s_add_u32 s8, s42, 0x1100
	s_addc_u32 s9, s43, 0
	s_add_u32 s12, s42, 0x1200
	s_addc_u32 s13, s43, 0
	s_waitcnt lgkmcnt(0)
	s_mul_i32 s3, s10, s24
	s_add_u32 s14, s42, 0x1300
	s_mul_i32 s3, s3, s11
	s_addc_u32 s15, s43, 0
	s_mov_b32 s10, 1
	v_mov_b32_e32 v17, 0
	s_branch .LBB0_1129

.LBB0_1643:
	s_cmp_gt_i32 s97, 5
	s_cselect_b64 s[4:5], -1, 0
	s_and_b64 s[0:1], s[64:65], s[4:5]
	s_andn2_b64 vcc, exec, s[0:1]
	s_cbranch_vccnz .LBB0_1697
	s_waitcnt vmcnt(0)
	s_barrier
	s_mov_b64 s[0:1], exec
	v_readlane_b32 s6, v238, 2
	v_readlane_b32 s7, v238, 3
	s_and_b64 s[6:7], s[0:1], s[6:7]
	s_mov_b64 exec, s[6:7]
	s_cbranch_execz .LBB0_1696
	s_add_i32 s3, 0, 0x25480
	v_mov_b32_e32 v1, s3
	s_waitcnt vmcnt(0) expcnt(0) lgkmcnt(0)
	buffer_inv sc1
	ds_read_b32 v3, v1
	s_add_i32 s3, 0, 0x25484
	v_mov_b32_e32 v1, s3
	ds_read_b32 v1, v1
	s_waitcnt lgkmcnt(1)
	v_cmp_ne_u32_e32 vcc, 0, v3
	s_cbranch_vccnz .LBB0_1660
	v_readlane_b32 s6, v238, 0
	v_readlane_b32 s7, v238, 1
	s_load_dwordx2 s[10:11], s[6:7], 0x4
	s_add_u32 s6, s42, 0x1000
	s_addc_u32 s7, s43, 0
	s_add_u32 s8, s42, 0x1100
	s_addc_u32 s9, s43, 0
	s_add_u32 s12, s42, 0x1200
	s_addc_u32 s13, s43, 0
	s_waitcnt lgkmcnt(0)
	s_mul_i32 s3, s10, s24
	s_add_u32 s14, s42, 0x1300
	s_mul_i32 s3, s3, s11
	s_addc_u32 s15, s43, 0
	s_mov_b32 s10, 1
	v_mov_b32_e32 v17, 0
	s_branch .LBB0_1648

.LBB0_1811:
	s_cmp_gt_i32 s97, 6
	s_cselect_b64 s[4:5], -1, 0
	s_and_b64 s[0:1], s[0:1], s[4:5]
	s_andn2_b64 vcc, exec, s[0:1]
	s_cbranch_vccnz .LBB0_1865
	s_waitcnt vmcnt(0)
	s_barrier
	s_mov_b64 s[0:1], exec
	v_readlane_b32 s6, v238, 2
	v_readlane_b32 s7, v238, 3
	s_and_b64 s[6:7], s[0:1], s[6:7]
	s_mov_b64 exec, s[6:7]
	s_cbranch_execz .LBB0_1864
	s_add_i32 s3, 0, 0x25480
	v_mov_b32_e32 v1, s3
	s_waitcnt vmcnt(0) expcnt(0) lgkmcnt(0)
	buffer_inv sc1
	ds_read_b32 v3, v1
	s_add_i32 s3, 0, 0x25484
	v_mov_b32_e32 v1, s3
	ds_read_b32 v1, v1
	s_waitcnt lgkmcnt(1)
	v_cmp_ne_u32_e32 vcc, 0, v3
	s_cbranch_vccnz .LBB0_1828
	v_readlane_b32 s6, v238, 0
	v_readlane_b32 s7, v238, 1
	s_load_dwordx2 s[10:11], s[6:7], 0x4
	s_add_u32 s6, s42, 0x1000
	s_addc_u32 s7, s43, 0
	s_add_u32 s8, s42, 0x1100
	s_addc_u32 s9, s43, 0
	s_add_u32 s12, s42, 0x1200
	s_addc_u32 s13, s43, 0
	s_waitcnt lgkmcnt(0)
	s_mul_i32 s3, s10, s24
	s_add_u32 s14, s42, 0x1300
	s_mul_i32 s3, s3, s11
	s_addc_u32 s15, s43, 0
	s_mov_b32 s10, 1
	v_mov_b32_e32 v17, 0
	s_branch .LBB0_1816

.LBB0_1939:
	s_cmp_gt_i32 s97, 7
	s_cselect_b64 s[0:1], -1, 0
	s_and_b64 s[4:5], s[12:13], s[0:1]
	s_andn2_b64 vcc, exec, s[4:5]
	s_cbranch_vccnz .LBB0_1993
	s_waitcnt vmcnt(0)
	s_barrier
	s_mov_b64 s[4:5], exec
	v_readlane_b32 s6, v238, 2
	v_readlane_b32 s7, v238, 3
	s_and_b64 s[6:7], s[4:5], s[6:7]
	s_mov_b64 exec, s[6:7]
	s_cbranch_execz .LBB0_1992
	s_add_i32 s3, 0, 0x25480
	v_mov_b32_e32 v1, s3
	s_waitcnt vmcnt(0) expcnt(0) lgkmcnt(0)
	buffer_inv sc1
	ds_read_b32 v3, v1
	s_add_i32 s3, 0, 0x25484
	v_mov_b32_e32 v1, s3
	ds_read_b32 v1, v1
	s_waitcnt lgkmcnt(1)
	v_cmp_ne_u32_e32 vcc, 0, v3
	s_cbranch_vccnz .LBB0_1956
	v_readlane_b32 s6, v238, 0
	v_readlane_b32 s7, v238, 1
	s_load_dwordx2 s[10:11], s[6:7], 0x4
	s_add_u32 s6, s42, 0x1000
	s_addc_u32 s7, s43, 0
	s_add_u32 s8, s42, 0x1100
	s_addc_u32 s9, s43, 0
	s_add_u32 s12, s42, 0x1200
	s_addc_u32 s13, s43, 0
	s_waitcnt lgkmcnt(0)
	s_mul_i32 s3, s10, s24
	s_add_u32 s14, s42, 0x1300
	s_mul_i32 s3, s3, s11
	s_addc_u32 s15, s43, 0
	s_mov_b32 s10, 1
	v_mov_b32_e32 v17, 0
	s_branch .LBB0_1944

.LBB0_2032:
	s_cmp_gt_i32 s97, 8
	s_cselect_b64 s[4:5], -1, 0
	s_and_b64 s[0:1], s[6:7], s[4:5]
	s_andn2_b64 vcc, exec, s[0:1]
	s_cbranch_vccnz .LBB0_2086
	s_waitcnt vmcnt(0)
	s_barrier
	s_mov_b64 s[0:1], exec
	v_readlane_b32 s6, v238, 2
	v_readlane_b32 s7, v238, 3
	s_and_b64 s[6:7], s[0:1], s[6:7]
	s_mov_b64 exec, s[6:7]
	s_cbranch_execz .LBB0_2085
	s_add_i32 s3, 0, 0x25480
	v_mov_b32_e32 v1, s3
	s_waitcnt vmcnt(0) expcnt(0) lgkmcnt(0)
	buffer_inv sc1
	ds_read_b32 v3, v1
	s_add_i32 s3, 0, 0x25484
	v_mov_b32_e32 v1, s3
	ds_read_b32 v1, v1
	s_waitcnt lgkmcnt(1)
	v_cmp_ne_u32_e32 vcc, 0, v3
	s_cbranch_vccnz .LBB0_2049
	v_readlane_b32 s6, v238, 0
	v_readlane_b32 s7, v238, 1
	s_load_dwordx2 s[10:11], s[6:7], 0x4
	s_add_u32 s6, s42, 0x1000
	s_addc_u32 s7, s43, 0
	s_add_u32 s8, s42, 0x1100
	s_addc_u32 s9, s43, 0
	s_add_u32 s12, s42, 0x1200
	s_addc_u32 s13, s43, 0
	s_waitcnt lgkmcnt(0)
	s_mul_i32 s3, s10, s24
	s_add_u32 s14, s42, 0x1300
	s_mul_i32 s3, s3, s11
	s_addc_u32 s15, s43, 0
	s_mov_b32 s10, 1
	v_mov_b32_e32 v17, 0
	s_branch .LBB0_2037

.LBB0_2889:
	s_cmp_gt_i32 s97, 9
	s_cselect_b64 s[6:7], -1, 0
	s_and_b64 s[0:1], s[0:1], s[6:7]
	s_andn2_b64 vcc, exec, s[0:1]
	s_cbranch_vccnz .LBB0_2943
	s_waitcnt vmcnt(0)
	s_barrier
	s_mov_b64 s[0:1], exec
	v_readlane_b32 s4, v238, 2
	v_readlane_b32 s5, v238, 3
	s_and_b64 s[4:5], s[0:1], s[4:5]
	s_mov_b64 exec, s[4:5]
	s_cbranch_execz .LBB0_2942
	s_add_i32 s3, 0, 0x25480
	v_mov_b32_e32 v1, s3
	s_waitcnt vmcnt(0) expcnt(0) lgkmcnt(0)
	buffer_inv sc1
	ds_read_b32 v3, v1
	s_add_i32 s3, 0, 0x25484
	v_mov_b32_e32 v1, s3
	ds_read_b32 v1, v1
	s_waitcnt lgkmcnt(1)
	v_cmp_ne_u32_e32 vcc, 0, v3
	s_cbranch_vccnz .LBB0_2906
	v_readlane_b32 s4, v238, 0
	v_readlane_b32 s5, v238, 1
	s_load_dwordx2 s[10:11], s[4:5], 0x4
	s_add_u32 s4, s42, 0x1000
	s_addc_u32 s5, s43, 0
	s_add_u32 s8, s42, 0x1100
	s_addc_u32 s9, s43, 0
	s_add_u32 s12, s42, 0x1200
	s_addc_u32 s13, s43, 0
	s_waitcnt lgkmcnt(0)
	s_mul_i32 s3, s10, s24
	s_add_u32 s14, s42, 0x1300
	s_mul_i32 s3, s3, s11
	s_addc_u32 s15, s43, 0
	s_mov_b32 s10, 1
	v_mov_b32_e32 v17, 0
	s_branch .LBB0_2894

.LBB0_2906:
	s_mov_b64 s[8:9], exec
	v_readlane_b32 s3, v238, 4
	s_lshl_b32 s3, s3, 8
	v_mbcnt_lo_u32_b32 v2, s8, 0
	s_add_u32 s4, s42, s3
	v_mbcnt_hi_u32_b32 v2, s9, v2
	s_addc_u32 s5, s43, 0
	v_cmp_eq_u32_e32 vcc, 0, v2
	s_and_saveexec_b64 s[12:13], vcc
	s_cbranch_execz .LBB0_2908
	s_bcnt1_i32_b64 s3, s[8:9]
	v_mov_b32_e32 v4, 0x1000
	v_mov_b32_e32 v5, s3
	s_waitcnt vmcnt(0)
	global_atomic_add v4, v4, v5, s[4:5] offset:1024 sc0

.LBB0_2969:
	s_cmp_gt_i32 s97, 10
	s_cselect_b64 s[6:7], -1, 0
	s_and_b64 s[0:1], s[4:5], s[6:7]
	s_andn2_b64 vcc, exec, s[0:1]
	s_cbranch_vccnz .LBB0_3023
	s_waitcnt vmcnt(0)
	s_barrier
	s_mov_b64 s[0:1], exec
	v_readlane_b32 s4, v238, 2
	v_readlane_b32 s5, v238, 3
	s_and_b64 s[4:5], s[0:1], s[4:5]
	s_mov_b64 exec, s[4:5]
	s_cbranch_execz .LBB0_3022
	s_add_i32 s3, 0, 0x25480
	v_mov_b32_e32 v1, s3
	s_waitcnt vmcnt(0) expcnt(0) lgkmcnt(0)
	buffer_inv sc1
	ds_read_b32 v3, v1
	s_add_i32 s3, 0, 0x25484
	v_mov_b32_e32 v1, s3
	ds_read_b32 v1, v1
	s_waitcnt lgkmcnt(1)
	v_cmp_ne_u32_e32 vcc, 0, v3
	s_cbranch_vccnz .LBB0_2986
	v_readlane_b32 s4, v238, 0
	v_readlane_b32 s5, v238, 1
	s_load_dwordx2 s[10:11], s[4:5], 0x4
	s_add_u32 s4, s42, 0x1000
	s_addc_u32 s5, s43, 0
	s_add_u32 s8, s42, 0x1100
	s_addc_u32 s9, s43, 0
	s_add_u32 s12, s42, 0x1200
	s_addc_u32 s13, s43, 0
	s_waitcnt lgkmcnt(0)
	s_mul_i32 s3, s10, s24
	s_add_u32 s14, s42, 0x1300
	s_mul_i32 s3, s3, s11
	s_addc_u32 s15, s43, 0
	s_mov_b32 s10, 1
	v_mov_b32_e32 v17, 0
	s_branch .LBB0_2974

.LBB0_3085:
	s_cmp_gt_i32 s97, 11
	s_cselect_b64 s[4:5], -1, 0
	s_and_b64 s[0:1], s[0:1], s[4:5]
	s_andn2_b64 vcc, exec, s[0:1]
	s_cbranch_vccnz .LBB0_3241
	s_waitcnt vmcnt(0)
	s_barrier
	s_mov_b64 s[0:1], exec
	v_readlane_b32 s6, v238, 2
	v_readlane_b32 s7, v238, 3
	s_and_b64 s[6:7], s[0:1], s[6:7]
	s_mov_b64 exec, s[6:7]
	s_cbranch_execz .LBB0_3240
	s_add_i32 s3, 0, 0x25480
	v_mov_b32_e32 v1, s3
	s_waitcnt vmcnt(0) expcnt(0) lgkmcnt(0)
	buffer_inv sc1
	ds_read_b32 v3, v1
	s_add_i32 s3, 0, 0x25484
	v_mov_b32_e32 v1, s3
	ds_read_b32 v1, v1
	s_waitcnt lgkmcnt(1)
	v_cmp_ne_u32_e32 vcc, 0, v3
	s_cbranch_vccnz .LBB0_3204
	v_readlane_b32 s6, v238, 0
	v_readlane_b32 s7, v238, 1
	s_load_dwordx2 s[10:11], s[6:7], 0x4
	s_add_u32 s6, s42, 0x1000
	s_addc_u32 s7, s43, 0
	s_add_u32 s8, s42, 0x1100
	s_addc_u32 s9, s43, 0
	s_add_u32 s12, s42, 0x1200
	s_addc_u32 s13, s43, 0
	s_waitcnt lgkmcnt(0)
	s_mul_i32 s3, s10, s24
	s_add_u32 s14, s42, 0x1300
	s_mul_i32 s3, s3, s11
	s_addc_u32 s15, s43, 0
	s_mov_b32 s10, 1
	v_mov_b32_e32 v17, 0
	s_branch .LBB0_3090

.LBB0_3686:
	s_cmp_gt_i32 s97, 12
	s_cselect_b64 s[4:5], -1, 0
	s_and_b64 s[0:1], s[62:63], s[4:5]
	s_andn2_b64 vcc, exec, s[0:1]
	s_cbranch_vccnz .LBB0_3740
	s_waitcnt vmcnt(0)
	s_barrier
	s_mov_b64 s[0:1], exec
	v_readlane_b32 s6, v238, 2
	v_readlane_b32 s7, v238, 3
	s_and_b64 s[6:7], s[0:1], s[6:7]
	s_mov_b64 exec, s[6:7]
	s_cbranch_execz .LBB0_3739
	s_add_i32 s3, 0, 0x25480
	v_mov_b32_e32 v1, s3
	s_waitcnt vmcnt(0) expcnt(0) lgkmcnt(0)
	buffer_inv sc1
	ds_read_b32 v3, v1
	s_add_i32 s3, 0, 0x25484
	v_mov_b32_e32 v1, s3
	ds_read_b32 v1, v1
	s_waitcnt lgkmcnt(1)
	v_cmp_ne_u32_e32 vcc, 0, v3
	s_cbranch_vccnz .LBB0_3703
	v_readlane_b32 s6, v238, 0
	v_readlane_b32 s7, v238, 1
	s_load_dwordx2 s[10:11], s[6:7], 0x4
	s_add_u32 s6, s42, 0x1000
	s_addc_u32 s7, s43, 0
	s_add_u32 s8, s42, 0x1100
	s_addc_u32 s9, s43, 0
	s_add_u32 s12, s42, 0x1200
	s_addc_u32 s13, s43, 0
	s_waitcnt lgkmcnt(0)
	s_mul_i32 s3, s10, s24
	s_add_u32 s14, s42, 0x1300
	s_mul_i32 s3, s3, s11
	s_addc_u32 s15, s43, 0
	s_mov_b32 s10, 1
	v_mov_b32_e32 v17, 0
	s_branch .LBB0_3691

.LBB0_3848:
	s_cmp_gt_i32 s97, 13
	s_cselect_b64 s[4:5], -1, 0
	s_and_b64 s[0:1], s[0:1], s[4:5]
	s_andn2_b64 vcc, exec, s[0:1]
	s_cbranch_vccnz .LBB0_3902
	s_waitcnt vmcnt(0)
	s_barrier
	s_mov_b64 s[0:1], exec
	v_readlane_b32 s6, v238, 2
	v_readlane_b32 s7, v238, 3
	s_and_b64 s[6:7], s[0:1], s[6:7]
	s_mov_b64 exec, s[6:7]
	s_cbranch_execz .LBB0_3901
	s_add_i32 s3, 0, 0x25480
	v_mov_b32_e32 v1, s3
	s_waitcnt vmcnt(0) expcnt(0) lgkmcnt(0)
	buffer_inv sc1
	ds_read_b32 v3, v1
	s_add_i32 s3, 0, 0x25484
	v_mov_b32_e32 v1, s3
	ds_read_b32 v1, v1
	s_waitcnt lgkmcnt(1)
	v_cmp_ne_u32_e32 vcc, 0, v3
	s_cbranch_vccnz .LBB0_3865
	v_readlane_b32 s6, v238, 0
	v_readlane_b32 s7, v238, 1
	s_load_dwordx2 s[10:11], s[6:7], 0x4
	s_add_u32 s6, s42, 0x1000
	s_addc_u32 s7, s43, 0
	s_add_u32 s8, s42, 0x1100
	s_addc_u32 s9, s43, 0
	s_add_u32 s12, s42, 0x1200
	s_addc_u32 s13, s43, 0
	s_waitcnt lgkmcnt(0)
	s_mul_i32 s3, s10, s24
	s_add_u32 s14, s42, 0x1300
	s_mul_i32 s3, s3, s11
	s_addc_u32 s15, s43, 0
	s_mov_b32 s10, 1
	v_mov_b32_e32 v17, 0
	s_branch .LBB0_3853

.LBB0_3976:
	s_cmp_gt_i32 s97, 14
	s_cselect_b64 s[0:1], -1, 0
	s_and_b64 s[4:5], s[12:13], s[0:1]
	s_andn2_b64 vcc, exec, s[4:5]
	s_cbranch_vccnz .LBB0_4030
	s_waitcnt vmcnt(0)
	s_barrier
	s_mov_b64 s[4:5], exec
	v_readlane_b32 s6, v238, 2
	v_readlane_b32 s7, v238, 3
	s_and_b64 s[6:7], s[4:5], s[6:7]
	s_mov_b64 exec, s[6:7]
	s_cbranch_execz .LBB0_4029
	s_add_i32 s3, 0, 0x25480
	v_mov_b32_e32 v1, s3
	s_waitcnt vmcnt(0) expcnt(0) lgkmcnt(0)
	buffer_inv sc1
	ds_read_b32 v3, v1
	s_add_i32 s3, 0, 0x25484
	v_mov_b32_e32 v1, s3
	ds_read_b32 v1, v1
	s_waitcnt lgkmcnt(1)
	v_cmp_ne_u32_e32 vcc, 0, v3
	s_cbranch_vccnz .LBB0_3993
	v_readlane_b32 s6, v238, 0
	v_readlane_b32 s7, v238, 1
	s_load_dwordx2 s[10:11], s[6:7], 0x4
	s_add_u32 s6, s42, 0x1000
	s_addc_u32 s7, s43, 0
	s_add_u32 s8, s42, 0x1100
	s_addc_u32 s9, s43, 0
	s_add_u32 s12, s42, 0x1200
	s_addc_u32 s13, s43, 0
	s_waitcnt lgkmcnt(0)
	s_mul_i32 s3, s10, s24
	s_add_u32 s14, s42, 0x1300
	s_mul_i32 s3, s3, s11
	s_addc_u32 s15, s43, 0
	s_mov_b32 s10, 1
	v_mov_b32_e32 v17, 0
	s_branch .LBB0_3981

.LBB0_4067:
	s_cmp_gt_i32 s97, 15
	s_cselect_b64 s[4:5], -1, 0
	s_and_b64 s[0:1], s[6:7], s[4:5]
	s_andn2_b64 vcc, exec, s[0:1]
	s_cbranch_vccnz .LBB0_4121
	s_waitcnt vmcnt(0)
	s_barrier
	s_mov_b64 s[0:1], exec
	v_readlane_b32 s6, v238, 2
	v_readlane_b32 s7, v238, 3
	s_and_b64 s[6:7], s[0:1], s[6:7]
	s_mov_b64 exec, s[6:7]
	s_cbranch_execz .LBB0_4120
	s_add_i32 s3, 0, 0x25480
	v_mov_b32_e32 v1, s3
	s_waitcnt vmcnt(0) expcnt(0) lgkmcnt(0)
	buffer_inv sc1
	ds_read_b32 v3, v1
	s_add_i32 s3, 0, 0x25484
	v_mov_b32_e32 v1, s3
	ds_read_b32 v1, v1
	s_waitcnt lgkmcnt(1)
	v_cmp_ne_u32_e32 vcc, 0, v3
	s_cbranch_vccnz .LBB0_4084
	v_readlane_b32 s6, v238, 0
	v_readlane_b32 s7, v238, 1
	s_load_dwordx2 s[10:11], s[6:7], 0x4
	s_add_u32 s6, s42, 0x1000
	s_addc_u32 s7, s43, 0
	s_add_u32 s8, s42, 0x1100
	s_addc_u32 s9, s43, 0
	s_add_u32 s12, s42, 0x1200
	s_addc_u32 s13, s43, 0
	s_waitcnt lgkmcnt(0)
	s_mul_i32 s3, s10, s24
	s_add_u32 s14, s42, 0x1300
	s_mul_i32 s3, s3, s11
	s_addc_u32 s15, s43, 0
	s_mov_b32 s10, 1
	v_mov_b32_e32 v17, 0
	s_branch .LBB0_4072

.LBB0_4139:
	s_cmp_gt_i32 s97, 16
	s_cselect_b64 s[4:5], -1, 0
	s_and_b64 s[0:1], s[0:1], s[4:5]
	s_andn2_b64 vcc, exec, s[0:1]
	s_cbranch_vccnz .LBB0_4193
	s_waitcnt vmcnt(0)
	s_barrier
	s_mov_b64 s[0:1], exec
	v_readlane_b32 s6, v238, 2
	v_readlane_b32 s7, v238, 3
	s_and_b64 s[6:7], s[0:1], s[6:7]
	s_mov_b64 exec, s[6:7]
	s_cbranch_execz .LBB0_4192
	s_add_i32 s3, 0, 0x25480
	v_mov_b32_e32 v1, s3
	s_waitcnt vmcnt(0) expcnt(0) lgkmcnt(0)
	buffer_inv sc1
	ds_read_b32 v3, v1
	s_add_i32 s3, 0, 0x25484
	v_mov_b32_e32 v1, s3
	ds_read_b32 v1, v1
	s_waitcnt lgkmcnt(1)
	v_cmp_ne_u32_e32 vcc, 0, v3
	s_cbranch_vccnz .LBB0_4156
	v_readlane_b32 s6, v238, 0
	v_readlane_b32 s7, v238, 1
	s_load_dwordx2 s[10:11], s[6:7], 0x4
	s_add_u32 s6, s42, 0x1000
	s_addc_u32 s7, s43, 0
	s_add_u32 s8, s42, 0x1100
	s_addc_u32 s9, s43, 0
	s_waitcnt lgkmcnt(0)
	s_mul_i32 s3, s10, s24
	s_add_u32 s10, s42, 0x1200
	s_mul_i32 s3, s3, s11
	s_addc_u32 s11, s43, 0
	s_add_u32 s12, s42, 0x1300
	s_addc_u32 s13, s43, 0
	s_mov_b32 s20, 1
	v_mov_b32_e32 v17, 0
	s_branch .LBB0_4144

.LBB0_4156:
	s_mov_b64 s[8:9], exec
	v_readlane_b32 s3, v238, 4
	s_lshl_b32 s3, s3, 8
	v_mbcnt_lo_u32_b32 v2, s8, 0
	s_add_u32 s6, s42, s3
	v_mbcnt_hi_u32_b32 v2, s9, v2
	s_addc_u32 s7, s43, 0
	v_cmp_eq_u32_e32 vcc, 0, v2
	s_and_saveexec_b64 s[10:11], vcc
	s_cbranch_execz .LBB0_4158
	s_bcnt1_i32_b64 s3, s[8:9]
	v_mov_b32_e32 v4, 0x1000
	v_mov_b32_e32 v5, s3
	s_waitcnt vmcnt(0)
	global_atomic_add v4, v4, v5, s[6:7] offset:1024 sc0
